# copyshare3: v14 + K/V-projection CUs 96..159 keep 3 of their 4 w_in copy rounds; chain CU c copies round 7 of virtual CUs 2c,2c+1 before its w_out share
# speedup vs baseline: 1.0025x; 1.0025x over previous
; #define LAS __attribute__((address_space(3)))
; #define P (*({ CParams* q_ = kp; asm volatile("" : "+s"(q_)); q_; }))
; #define wave (__builtin_amdgcn_readfirstlane(tid >> 6))
; DI void ret_unit(CParams& P, int l, int u, LAS unsigned char* lds, int tid_, int lane_, int wave_) {
;     ...
;     const int hh = u & 3, b = u >> 2;
;     constexpr int LD = 264, LDP = 72, LDR = 256, IMG = 33792;
;     LAS bf16_t* Qs = (LAS bf16_t*)lds; LAS bf16_t* Ks = (LAS bf16_t*)(lds + IMG); LAS bf16_t* Vs = (LAS bf16_t*)(lds + 2 * IMG);
;     LAS bf16_t* Ps = (LAS bf16_t*)(lds + 3 * IMG); LAS bf16_t* R = (LAS bf16_t*)(lds + 3 * IMG + 9216);
;     const float g64 = exp2f(64.f * log2f(1.f - exp2f(-5.f - (float)hh)));
; __global__ void __launch_bounds__(NTHREADS, 2) fwd_megakernel(Params P_) {
;     ...
;         const float* rss_in = (const float*)(ws + (l == 0 ? WS_RSS0 : WS_RSS1));
;         float* rss_out = (float*)(ws + (l == 0 ? WS_RSS1 : WS_RSS2));
;         const pg8::Gemm g_in{(const bf16_t*)(ws + WS_XB), (const bf16_t*)(ws + WS_WIN) + (size_t)l * NPROJ * DM, MTOK, NPROJ, DM};
;         const pg8::EpiProj E_in{(bf16_t*)(ws + WS_PROJ), NPROJ, rss_in, 1.f / DM, EPS, 1, (const float*)(ws + WS_COS), (const float*)(ws + WS_SIN), (float*)(ws + WS_AVSTAT) + (size_t)l * MTOK * 2};
;         { const pg8::SubOrder S{16, 1024, 16, 24, 24, bx, G, 0};
;           pg8::gemm_phase<pg8::EpiProj, pg8::SubOrder, true, true>(lds, g_in, S, E_in); }
;         xcd_barrier(xbar);
;     ...
;         if (bx < 32) ret_unit(P, l, bx, lds, tid, lane, wave);
;     ...
;         { const pg8::SubOrder S{32, 2048, 24, 0, 16, bx, G, 1};
;           pg8::gemm_phase<pg8::EpiProj, pg8::SubOrder, true, true>(lds, g_in, S, E_in); }
;         { pg8::Gemm g{(const bf16_t*)(ws + WS_MEMB), (const bf16_t*)(ws + WS_WKV) + (size_t)l * NKV * DM, MROWS, NKV, DM}; pg8::StaticOrder S; S.init(MROWS, NKV, G, (bx >= 96 && bx < 160) ? bx - 96 : (1 << 20));
.LBB0_248:
	v_writelane_b32 v254, s42, 3
	s_nop 1
	v_writelane_b32 v254, s43, 4
	s_or_b64 exec, exec, s[38:39]
	s_add_u32 s50, s72, 0x12200000
	s_addc_u32 s51, s73, 0
	s_add_u32 s80, s72, 0x200000
	s_addc_u32 s83, s73, 0
	s_add_u32 s52, s72, 0x1a200000
	s_addc_u32 s53, s73, 0
	s_add_u32 s0, s72, 0x3ba00000
	s_addc_u32 s1, s73, 0
	v_writelane_b32 v254, s0, 5
	s_mov_b32 s33, 0xc2fc0000
	v_mov_b32_e32 v219, 0x42800000
	v_writelane_b32 v254, s1, 6
	s_add_u32 s0, s72, 0x3c200000
	s_addc_u32 s1, s73, 0
	s_add_u32 s88, s72, 0x40000
	s_addc_u32 s89, s73, 0
	s_cmpk_lt_i32 s69, 0x400
	v_writelane_b32 v254, s0, 7
	s_cselect_b64 s[8:9], -1, 0
	s_ashr_i32 s92, s69, 31
	v_writelane_b32 v254, s1, 8
	s_lshr_b32 s0, s92, 29
	s_add_i32 s2, s69, s0
	s_ashr_i32 s4, s2, 3
	s_lshl_b32 s0, s69, 7
	s_mul_i32 s1, s4, 0xfffffc01
	s_add_i32 s0, s1, s0
	s_ashr_i32 s1, s0, 31
	s_lshr_b32 s1, s1, 25
	s_add_i32 s1, s0, s1
	s_ashr_i32 s5, s1, 7
	s_and_b32 s1, s1, 0xffffff80
	s_sub_i32 s0, s0, s1
	s_bfe_i32 s1, s0, 0x80000
	s_bfe_u32 s1, s1, 0x3000c
	s_add_i32 s1, s0, s1
	s_bfe_i32 s6, s1, 0x80000
	s_and_b32 s6, 0xffff, s6
	s_and_b32 s1, s1, 0xf8
	s_lshr_b32 s6, s6, 3
	s_sub_i32 s0, s0, s1
	s_lshl_b32 s5, s5, 3
	s_sext_i32_i8 s0, s0
	s_add_i32 s6, s6, 24
	s_add_i32 s10, s5, s0
	s_and_b32 s6, s6, 0xff
	s_cmp_lt_i32 s69, 32
	s_cselect_b64 s[0:1], -1, 0
	s_and_b32 s5, s69, 3
	v_cvt_f32_ubyte0_e32 v0, s5
	v_sub_f32_e32 v0, 0xc0a00000, v0
	v_cmp_gt_f32_e32 vcc, s33, v0
	v_writelane_b32 v254, s0, 9
	s_mov_b32 s45, 0x800000
	v_cndmask_b32_e32 v1, 0, v219, vcc
	v_add_f32_e32 v0, v0, v1
	v_exp_f32_e32 v0, v0
	v_writelane_b32 v254, s1, 10
	s_and_b64 s[0:1], vcc, exec
	s_cselect_b32 s0, 0xffffffc0, 0
	v_ldexp_f32 v0, v0, s0
	v_sub_f32_e32 v0, 1.0, v0
	v_cmp_gt_f32_e32 vcc, s45, v0
	s_and_b64 s[0:1], vcc, exec
	s_cselect_b32 s0, 32, 0
	v_ldexp_f32 v0, v0, s0
	v_log_f32_e32 v0, v0
	v_mov_b32_e32 v220, 0x42000000
	v_cndmask_b32_e32 v1, 0, v220, vcc
	s_mul_i32 s0, s77, s76
	v_sub_f32_e32 v0, v0, v1
	v_mul_f32_e32 v1, 0x42800000, v0
	v_cmp_gt_f32_e32 vcc, s33, v1
	s_lshl_b32 s7, s5, 8
	s_mul_i32 s77, s0, s3
	v_cndmask_b32_e32 v1, 0, v219, vcc
	v_fmac_f32_e32 v1, 0x42800000, v0
	v_exp_f32_e32 v0, v1
	s_and_b64 s[0:1], vcc, exec
	s_cselect_b32 s0, 0xffffffc0, 0
	s_mov_b32 s97, 0
	v_ldexp_f32 v192, v0, s0
	s_lshl_b32 s0, s69, 9
	s_and_b32 s0, s0, 0xfffff800
	v_writelane_b32 v254, s0, 11
	s_cmp_gt_i32 s69, 31
	s_movk_i32 s0, 0xffe0
	s_cselect_b32 s0, s0, 0x700
	s_add_i32 s0, s0, s69
	s_ashr_i32 s1, s0, 31
	s_lshr_b32 s1, s1, 29
	s_add_i32 s1, s0, s1
	s_ashr_i32 s1, s1, 3
	s_lshl_b32 s0, s0, 8
	s_mulk_i32 s1, 0xf801
	s_add_i32 s0, s1, s0
	s_ashr_i32 s1, s0, 31
	s_lshr_b32 s1, s1, 24
	s_add_i32 s1, s0, s1
	s_ashr_i32 s3, s1, 8
	s_and_b32 s1, s1, 0xffffff00
	s_sub_i32 s0, s0, s1
	s_bfe_u32 s1, s0, 0x3001c
	s_add_i32 s1, s0, s1
	s_sext_i32_i16 s5, s1
	s_and_b32 s1, s1, 0xfff8
	s_sub_i32 s1, s0, s1
	s_lshl_b32 s3, s3, 3
	s_sext_i32_i16 s1, s1
	s_ashr_i32 s5, s5, 3
	s_add_i32 s12, s3, s1
	s_cmpk_lt_i32 s0, 0xc0
	s_cselect_b32 s0, 0, 16
	s_add_i32 s14, s0, s5
	s_mov_b32 s0, s12
	s_ashr_i32 s13, s12, 31
	v_writelane_b32 v254, s0, 12
	s_ashr_i32 s15, s14, 31
	v_mov_b32_e32 v0, 0x60
	v_writelane_b32 v254, s1, 13
	s_lshl_b64 s[0:1], s[12:13], 21
	s_mov_b32 s12, s14
	v_writelane_b32 v254, s12, 14
	s_movk_i32 s55, 0x6000
	v_mov_b32_e32 v194, v192
	v_writelane_b32 v254, s13, 15
	s_lshl_b64 s[12:13], s[14:15], 21
	v_writelane_b32 v254, s12, 16
	s_add_u32 s0, s50, s0
	s_addc_u32 s1, s51, s1
	v_writelane_b32 v254, s13, 17
	s_add_u32 s12, s0, 0x100000
	v_writelane_b32 v254, s0, 18
	s_addc_u32 s13, s1, 0
	v_mov_b32_e32 v195, v192
	v_writelane_b32 v254, s1, 19
	v_writelane_b32 v254, s12, 20
	s_add_i32 s0, s69, 0x700
	s_movk_i32 s81, 0x2000
	v_writelane_b32 v254, s13, 21
	v_writelane_b32 v254, s0, 22
	v_sub_co_u32_e64 v0, s[0:1], s69, v0
	s_nop 0
	v_readfirstlane_b32 s3, v0
	v_writelane_b32 v254, s0, 23
	v_mov_b32_e32 v197, 0
	v_mov_b32_e32 v222, 0x358637bd
	v_writelane_b32 v254, s1, 24
	s_add_i32 s0, s69, 0x7a0
	v_writelane_b32 v254, s0, 25
	s_sub_i32 s0, s69, 32
	s_add_u32 s5, s72, 0x3a200000
	s_addc_u32 s11, s73, 0
	v_writelane_b32 v254, s0, 26
	s_add_u32 s0, s72, 0x10200000
	v_writelane_b32 v254, s0, 27
	s_addc_u32 s0, s73, 0
	s_cmp_lt_u32 s3, 64
	v_writelane_b32 v254, s0, 28
	s_cselect_b64 s[0:1], -1, 0
	v_writelane_b32 v254, s0, 29
; #define P (*({ CParams* q_ = kp; asm volatile("" : "+s"(q_)); q_; }))
; __global__ void __launch_bounds__(NTHREADS, 2) fwd_megakernel(Params P_) {
;     ...
;         { pg8::Gemm g{(const bf16_t*)(ws + WS_MEMB), (const bf16_t*)(ws + WS_WKV) + (size_t)l * NKV * DM, MROWS, NKV, DM}; pg8::StaticOrder S; S.init(MROWS, NKV, G, (bx >= 96 && bx < 160) ? bx - 96 : (1 << 20));
;           pg8::EpiProj E{(bf16_t*)(ws + WS_KV), NKV, nullptr, 0.f, 0.f, 0, nullptr, nullptr, nullptr};
;           pg8::gemm_phase<pg8::EpiProj, pg8::StaticOrder, true, true>(lds, g, S, E); }
;         if (bx >= 160) { int t2 = threadIdx.x; asm volatile("" : "+v"(t2)); const int w2 = __builtin_amdgcn_readfirstlane(t2 >> 6);
;             convert_weights(P, 1, lds, (bx - 160) * NWAVES + w2, 96 * NWAVES, t2 & 63, w2, l == 0 ? 5 : 2); }
	v_mov_b32_e32 v223, 1
	s_mov_b32 s84, 0x3e0f83e1
	v_writelane_b32 v254, s1, 30
	s_and_b64 s[0:1], s[0:1], exec
	s_cselect_b32 s1, s3, 0x100000
	s_add_u32 s12, s72, 0x3b200000
	s_addc_u32 s13, s73, 0
	v_writelane_b32 v254, s12, 31
	s_bfe_u32 s3, s1, 0x30003
	s_lshr_b32 s0, s1, 3
	v_writelane_b32 v254, s13, 32
	v_writelane_b32 v254, s3, 33
	v_writelane_b32 v254, s1, 34
	s_and_b32 s1, s1, 7
	v_writelane_b32 v254, s1, 35
	s_lshl_b32 s1, s1, 21
	s_lshl_b32 s0, s0, 21
	v_writelane_b32 v254, s1, 36
	v_writelane_b32 v254, s5, 37
	s_add_u32 s0, s5, s0
	v_writelane_b32 v254, s11, 38
	s_addc_u32 s1, s11, 0
	s_add_u32 s12, s0, 0x100000
	v_writelane_b32 v254, s0, 39
	s_addc_u32 s13, s1, 0
	s_movk_i32 s85, 0xffdf
	v_writelane_b32 v254, s1, 40
	v_writelane_b32 v254, s12, 41
	s_ashr_i32 s0, s76, 31
	s_cmpk_gt_i32 s69, 0xffff
	v_writelane_b32 v254, s13, 42
	v_writelane_b32 v254, s0, 43
	s_cselect_b64 s[0:1], -1, 0
	v_writelane_b32 v254, s0, 44
	v_mov_b32_e32 v224, 0x3d800000
	v_not_b32_e32 v225, 63
	v_writelane_b32 v254, s1, 45
	s_add_i32 s0, s69, 0xffffffe0
	s_and_b32 s0, s0, 63
	s_add_i32 s98, s69, 0xffffff60
	s_cmpk_gt_i32 s69, 0xdf
	s_cselect_b32 s0, s98, s0
	s_lshl_b32 s98, s69, 1
	s_cmpk_lt_i32 s69, 0x20
	s_cselect_b32 s0, s98, s0
	s_lshl_b32 s0, s0, 3
	s_add_u32 s5, s72, 0x32200000
	s_addc_u32 s12, s73, 0
	v_writelane_b32 v254, s0, 46
	s_add_u32 s0, s72, 0xc200000
	v_writelane_b32 v254, s0, 47
	s_addc_u32 s0, s73, 0
	v_writelane_b32 v254, s0, 48
	s_and_b32 s0, s2, -8
	s_sub_i32 s2, s69, s0
	s_mov_b32 s0, s10
	v_writelane_b32 v254, s0, 49
	s_ashr_i32 s11, s10, 31
	s_lshl_b32 s3, s2, 7
	v_writelane_b32 v254, s1, 50
	s_lshl_b64 s[0:1], s[10:11], 21
	v_writelane_b32 v254, s6, 51
	s_lshl_b32 s6, s6, 21
	s_add_u32 s0, s50, s0
	s_addc_u32 s1, s51, s1
	v_writelane_b32 v254, s6, 52
	s_add_u32 s10, s0, 0x100000
	v_writelane_b32 v254, s0, 53
	s_addc_u32 s11, s1, 0
	s_cmp_lt_i32 s2, 0
	s_mulk_i32 s2, 0x81
	v_writelane_b32 v254, s1, 54
	s_cselect_b32 s0, s2, s3
	s_add_i32 s0, s0, s4
	s_ashr_i32 s1, s0, 31
	s_lshr_b32 s1, s1, 25
	s_add_i32 s1, s0, s1
	s_ashr_i32 s2, s1, 7
	s_and_b32 s1, s1, 0xff80
	s_sub_i32 s1, s0, s1
	s_bfe_i32 s0, s1, 0x80000
	s_bfe_u32 s0, s0, 0x3000c
	s_add_i32 s3, s1, s0
	s_bfe_i32 s0, s3, 0x80000
	s_and_b32 s3, s3, 0xf8
	s_sub_i32 s1, s1, s3
	v_writelane_b32 v254, s10, 55
	s_lshl_b32 s2, s2, 3
	s_sext_i32_i16 s4, s0
	s_sext_i32_i8 s1, s1
	v_writelane_b32 v254, s11, 56
	s_add_i32 s10, s2, s1
	s_ashr_i32 s1, s4, 3
	s_lshr_b32 s0, s4, 3
	v_writelane_b32 v254, s1, 57
	s_mov_b32 s2, s10
	v_writelane_b32 v254, s2, 58
	s_bfe_i64 s[0:1], s[0:1], 0x100000
	s_ashr_i32 s11, s10, 31
	v_writelane_b32 v254, s3, 59
	s_lshl_b64 s[0:1], s[0:1], 21
	s_lshl_b64 s[2:3], s[10:11], 21
	v_writelane_b32 v254, s0, 60
	v_mbcnt_hi_u32_b32 v226, -1, v71
	v_mov_b32_e32 v227, 0x840
	v_writelane_b32 v254, s1, 61
	s_add_u32 s0, s5, s2
	s_addc_u32 s1, s12, s3
	s_add_u32 s2, s0, 0x100000
	v_writelane_b32 v255, s0, 0
	s_addc_u32 s3, s1, 0
	v_writelane_b32 v254, s5, 62
	v_writelane_b32 v255, s1, 1
	v_writelane_b32 v255, s2, 2
	s_add_i32 s0, 0, 0x27f20
	v_writelane_b32 v254, s12, 63
	v_writelane_b32 v255, s3, 3
	v_writelane_b32 v255, s8, 4
	s_movk_i32 s93, 0x210
	s_movk_i32 s79, 0x7fff
	v_writelane_b32 v255, s9, 5
	v_writelane_b32 v255, s0, 6
	s_add_i32 s0, 0, 0x27f24
	v_writelane_b32 v255, s0, 7
	s_add_i32 s0, 0, 0x1b000
	v_writelane_b32 v255, s0, 8
	s_add_i32 s0, 0, 0x18c00
	v_writelane_b32 v255, s0, 9
	v_writelane_b32 v255, s7, 10
	v_writelane_b32 v255, s72, 11
	v_cndmask_b32_e64 v221, 0, 1, s[8:9]
	s_lshl_b32 s16, s7, 1
	v_writelane_b32 v255, s73, 12
	v_writelane_b32 v255, s74, 13
	s_mov_b32 s57, 0x32201000
	s_movk_i32 s43, 0x1000
	v_writelane_b32 v255, s75, 14
	v_writelane_b32 v255, s69, 15
	v_writelane_b32 v255, s76, 16
	s_mov_b32 s70, 0x1a202000
	s_mov_b32 s71, 0x32200000
	v_writelane_b32 v255, s77, 17
	v_writelane_b32 v255, s78, 18
	v_writelane_b32 v255, s86, 19
	s_movk_i32 s56, 0x110
	s_add_i32 s4, 0, 0x11000
	v_writelane_b32 v255, s87, 20
	v_writelane_b32 v255, s80, 21
	v_writelane_b32 v255, s83, 22
	v_writelane_b32 v255, s88, 23
	v_writelane_b32 v255, s89, 24
	v_writelane_b32 v255, s92, 25
	s_movk_i32 s5, 0x5000
	s_mov_b64 s[0:1], -1
	s_mov_b64 s[60:61], 0x80
	s_mov_b32 s82, 0x3a800000
	s_mov_b32 s62, s97
	v_writelane_b32 v255, s77, 26
	s_waitcnt lgkmcnt(0)
	s_barrier
	s_branch .LBB0_251

; #define LAS __attribute__((address_space(3)))
; #define P (*({ CParams* q_ = kp; asm volatile("" : "+s"(q_)); q_; }))
; #define wave (__builtin_amdgcn_readfirstlane(tid >> 6))
;     unsigned char* ws = P.ws;
;     LAS float* scr = (LAS float*)(lds + wave * 16384);
;     constexpr int I_IN = (DM / 64) * (NPROJ / 32), I_OUT = (DM / 64) * (DM / 32), I_KV = (DM / 64) * (NKV / 32);
;     if (which & 1) p0_matrix(P.w_in + (size_t)l * DM * NPROJ, P.norm_g + l * DM, DM, NPROJ, (bf16_t*)(ws + WS_WIN) + (size_t)l * NPROJ * DM, scr, I_IN, gw, NGW, lane);
;     if (which & 2) p0_matrix(P.w_out + (size_t)l * DM * DM, nullptr, DM, DM, (bf16_t*)(ws + WS_WOUT) + (size_t)l * DM * DM, scr, I_OUT, gw, NGW, lane);
;     if (which & 4) p0_matrix(P.w_kv + (size_t)l * DM * NKV, P.mem_ng + l * DM, DM, NKV, (bf16_t*)(ws + WS_WKV) + (size_t)l * NKV * DM, scr, I_KV, gw, NGW, lane);
; __global__ void __launch_bounds__(NTHREADS, 2) fwd_megakernel(Params P_) {
;     ...
;         if (bx >= 160) { int t2 = threadIdx.x; asm volatile("" : "+v"(t2)); const int w2 = __builtin_amdgcn_readfirstlane(t2 >> 6);
;             convert_weights(P, 1, lds, (bx - 160) * NWAVES + w2, 96 * NWAVES, t2 & 63, w2, l == 0 ? 5 : 2); }
.Lcopy_cls_lo:
	s_cmpk_lt_i32 s69, 0x20
	s_cbranch_scc0 .Lcopy_cls_mid
	s_and_b32 s1, s1, 3
	s_movk_i32 s98, 0x5400
	s_mov_b32 s101, 0
	s_branch .Lcopy_cls_done

; #define LAS __attribute__((address_space(3)))
; #define P (*({ CParams* q_ = kp; asm volatile("" : "+s"(q_)); q_; }))
; #define wave (__builtin_amdgcn_readfirstlane(tid >> 6))
;     unsigned char* ws = P.ws;
;     LAS float* scr = (LAS float*)(lds + wave * 16384);
;     constexpr int I_IN = (DM / 64) * (NPROJ / 32), I_OUT = (DM / 64) * (DM / 32), I_KV = (DM / 64) * (NKV / 32);
;     if (which & 1) p0_matrix(P.w_in + (size_t)l * DM * NPROJ, P.norm_g + l * DM, DM, NPROJ, (bf16_t*)(ws + WS_WIN) + (size_t)l * NPROJ * DM, scr, I_IN, gw, NGW, lane);
;     if (which & 2) p0_matrix(P.w_out + (size_t)l * DM * DM, nullptr, DM, DM, (bf16_t*)(ws + WS_WOUT) + (size_t)l * DM * DM, scr, I_OUT, gw, NGW, lane);
;     if (which & 4) p0_matrix(P.w_kv + (size_t)l * DM * NKV, P.mem_ng + l * DM, DM, NKV, (bf16_t*)(ws + WS_WKV) + (size_t)l * NKV * DM, scr, I_KV, gw, NGW, lane);
; __global__ void __launch_bounds__(NTHREADS, 2) fwd_megakernel(Params P_) {
;     ...
;         if (bx >= 160) { int t2 = threadIdx.x; asm volatile("" : "+v"(t2)); const int w2 = __builtin_amdgcn_readfirstlane(t2 >> 6);
;             convert_weights(P, 1, lds, (bx - 160) * NWAVES + w2, 96 * NWAVES, t2 & 63, w2, l == 0 ? 5 : 2); }
.Lcopy_cls_hi:
	s_movk_i32 s98, 0x3000
	s_movk_i32 s99, 0x4800

; #define LAS __attribute__((address_space(3)))
; #define P (*({ CParams* q_ = kp; asm volatile("" : "+s"(q_)); q_; }))
; #define wave (__builtin_amdgcn_readfirstlane(tid >> 6))
; DI void p0_matrix(const float* W, const float* gain, int K, int N, bf16_t* WT, LAS float* scr, int nitems, int gw, int NGW, int lane) {
;     for (int it = gw; it < nitems; it += 4 * NGW) {
;         const int it2 = it + NGW, it3 = it + 2 * NGW, it4 = it + 3 * NGW; const bool h2 = it2 < nitems, h3 = it3 < nitems, h4 = it4 < nitems;
;         f32x4 va[8], vb[8], vc[8], vd[8];
;         p0_item_load(W, N, it, lane, va);
;         if (h2) p0_item_load(W, N, it2, lane, vb);
;         if (h3) p0_item_load(W, N, it3, lane, vc);
;         if (h4) p0_item_load(W, N, it4, lane, vd);
;         p0_item_store(va, gain, K, N, WT, scr, it, lane);
;         if (h2) p0_item_store(vb, gain, K, N, WT, scr, it2, lane);
;         if (h3) p0_item_store(vc, gain, K, N, WT, scr, it3, lane);
;         if (h4) p0_item_store(vd, gain, K, N, WT, scr, it4, lane);
;     }
; }
;     unsigned char* ws = P.ws;
;     LAS float* scr = (LAS float*)(lds + wave * 16384);
;     constexpr int I_IN = (DM / 64) * (NPROJ / 32), I_OUT = (DM / 64) * (DM / 32), I_KV = (DM / 64) * (NKV / 32);
;     if (which & 1) p0_matrix(P.w_in + (size_t)l * DM * NPROJ, P.norm_g + l * DM, DM, NPROJ, (bf16_t*)(ws + WS_WIN) + (size_t)l * NPROJ * DM, scr, I_IN, gw, NGW, lane);
.Lcopy_win_again:
	s_cmpk_gt_i32 s6, 0x5fff
	s_cbranch_scc1 .LBB0_598
	s_load_dwordx4 s[20:23], s[12:13], 0x18
	v_lshlrev_b32_e32 v0, 4, v140
	v_and_b32_e32 v196, 0x70, v0
	s_mov_b64 s[2:3], 0xc000000
	v_lshrrev_b32_e32 v141, 3, v140
	s_waitcnt lgkmcnt(0)
	v_lshl_add_u64 v[0:1], s[22:23], 0, v[196:197]
	v_lshl_add_u64 v[132:133], v[0:1], 0, s[2:3]
	v_lshlrev_b32_e32 v0, 3, v140
	v_and_b32_e32 v0, 56, v0
	s_add_u32 s14, s20, 0x4000
	v_add_u32_e32 v2, s0, v196
	s_movk_i32 s2, 0x84
	v_lshlrev_b32_e32 v196, 1, v0
	s_addc_u32 s15, s21, 0
	v_mad_u32_u24 v4, v141, s2, v227
	v_mul_u32_u24_e32 v5, 0x84, v0
	v_lshl_add_u64 v[0:1], s[10:11], 0, v[196:197]
	s_mov_b64 s[2:3], 0x6200000
	s_cmp_lg_u64 s[20:21], 0
	v_mul_u32_u24_e32 v3, 0x84, v141
	v_lshl_add_u64 v[134:135], v[0:1], 0, s[2:3]
	v_lshlrev_b32_e32 v0, 2, v141
	s_cselect_b64 s[18:19], -1, 0
	v_or_b32_e32 v142, 8, v141
	v_or_b32_e32 v143, 16, v141
	v_or_b32_e32 v144, 24, v141
	v_or_b32_e32 v145, 32, v141
	v_or_b32_e32 v146, 40, v141
	v_or_b32_e32 v147, 48, v141
	v_or_b32_e32 v148, 56, v141
	v_add3_u32 v149, s0, v5, v0
	s_add_i32 s3, s6, s98
	s_lshl_b32 s2, s3, 5
	v_add_u32_e32 v150, v2, v3
	v_add_u32_e32 v151, v2, v4
	s_branch .LBB0_523

; #define LAS __attribute__((address_space(3)))
; #define P (*({ CParams* q_ = kp; asm volatile("" : "+s"(q_)); q_; }))
; #define wave (__builtin_amdgcn_readfirstlane(tid >> 6))
;     unsigned char* ws = P.ws;
;     LAS float* scr = (LAS float*)(lds + wave * 16384);
;     constexpr int I_IN = (DM / 64) * (NPROJ / 32), I_OUT = (DM / 64) * (DM / 32), I_KV = (DM / 64) * (NKV / 32);
;     if (which & 1) p0_matrix(P.w_in + (size_t)l * DM * NPROJ, P.norm_g + l * DM, DM, NPROJ, (bf16_t*)(ws + WS_WIN) + (size_t)l * NPROJ * DM, scr, I_IN, gw, NGW, lane);
;     if (which & 2) p0_matrix(P.w_out + (size_t)l * DM * DM, nullptr, DM, DM, (bf16_t*)(ws + WS_WOUT) + (size_t)l * DM * DM, scr, I_OUT, gw, NGW, lane);
;     if (which & 4) p0_matrix(P.w_kv + (size_t)l * DM * NKV, P.mem_ng + l * DM, DM, NKV, (bf16_t*)(ws + WS_WKV) + (size_t)l * NKV * DM, scr, I_KV, gw, NGW, lane);
; __global__ void __launch_bounds__(NTHREADS, 2) fwd_megakernel(Params P_) {
;     ...
;         if (bx >= 160) { int t2 = threadIdx.x; asm volatile("" : "+v"(t2)); const int w2 = __builtin_amdgcn_readfirstlane(t2 >> 6);
;             convert_weights(P, 1, lds, (bx - 160) * NWAVES + w2, 96 * NWAVES, t2 & 63, w2, l == 0 ? 5 : 2); }
.LBB0_598:
	s_bitcmp0_b32 s1, 0
	s_cbranch_scc1 .Lcopy_wout
	s_cmpk_lt_i32 s69, 0x20
	s_cbranch_scc0 .Lcopy_wout
	s_cmp_eq_u32 s101, 0
	s_cbranch_scc0 .Lcopy_chain_wout
	s_mov_b32 s101, 1
	s_add_i32 s6, s6, 8
	s_branch .Lcopy_win_again
.Lcopy_chain_wout:
	s_cmp_eq_u32 s101, 1
	s_cbranch_scc0 .Lcopy_wout
	s_mov_b32 s101, 2
	s_lshl_b32 s2, s69, 3
	s_sub_i32 s6, s6, s2
	s_addk_i32 s6, 0x1f8
